# FFT stage-1 DFT table staged once per phase B in LDS; fft1m B fragments via ds_read_b128; fft1m loads batched
# speedup vs baseline: 1.1326x; 1.0104x over previous
.LBB0_448:
	s_and_b64 vcc, exec, s[0:1]
	s_cbranch_vccz .LBB0_559
	v_lshlrev_b32_e32 v64, 4, v0
	v_readlane_b32 s4, v253, 41
	v_readlane_b32 s5, v253, 42
	v_lshrrev_b32_e32 v65, 3, v0
	v_and_b32_e32 v76, 7, v0
	v_mul_u32_u24_e32 v65, 0x90, v65
	v_lshl_add_u32 v65, v76, 4, v65
	v_add_u32_e32 v65, 0x4000, v65
	s_nop 4
	global_load_dwordx4 v[72:75], v64, s[4:5]
	v_add_u32_e32 v76, 0x1000, v64
	global_load_dwordx4 v[84:87], v76, s[4:5]
	v_add_u32_e32 v76, 0x2000, v64
	global_load_dwordx4 v[88:91], v76, s[4:5]
	v_add_u32_e32 v76, 0x3000, v64
	global_load_dwordx4 v[92:95], v76, s[4:5]
	s_waitcnt vmcnt(0)
	ds_write_b128 v65, v[72:75]
	ds_write_b128 v65, v[84:87] offset:4608
	ds_write_b128 v65, v[88:91] offset:9216
	ds_write_b128 v65, v[92:95] offset:13824
	s_waitcnt lgkmcnt(0)
	s_barrier
	s_and_saveexec_b64 s[0:1], s[12:13]
	s_cbranch_execz .LBB0_453
	s_mov_b64 s[4:5], exec
	v_mbcnt_lo_u32_b32 v1, s4, 0
	v_mbcnt_hi_u32_b32 v1, s5, v1
	v_cmp_eq_u32_e32 vcc, 0, v1
	s_and_saveexec_b64 s[2:3], vcc
	s_cbranch_execz .LBB0_452
	s_bcnt1_i32_b64 s4, s[4:5]
	s_waitcnt vmcnt(0)
	v_mov_b32_e32 v2, s4
	v_readlane_b32 s4, v254, 43
	v_readlane_b32 s5, v254, 44
	s_nop 4
	global_atomic_add v2, v131, v2, s[4:5] sc0

.LBB0_540:
	s_andn2_b64 vcc, exec, s[0:1]
	s_cbranch_vccnz .LBB0_542
	s_sub_i32 s0, s21, s16
	s_bfe_u32 s1, s0, 0x60003
	s_lshl_b32 s0, s0, 3
	v_mov_b32_e32 v1, v0
	s_lshl_b32 s2, s21, 6
	s_and_b32 s0, s0, 0xfffff000
	s_and_b32 s2, s2, 0x1c0
	s_waitcnt vmcnt(0) lgkmcnt(0)
	v_lshlrev_b32_e32 v72, 3, v1
	s_or_b32 s10, s1, s0
	s_lshl_b32 s11, s2, 1
	v_readlane_b32 s14, v253, 53
	v_and_b32_e32 v73, 56, v72
	v_and_b32_e32 v74, 0xffffffc0, v72
	v_readlane_b32 s15, v253, 54
	s_add_u32 s18, s14, s11
	v_add_u32_e32 v72, s10, v74
	s_addc_u32 s10, s15, 0
	v_lshlrev_b32_e32 v74, 1, v73
	v_ashrrev_i32_e32 v73, 31, v72
	s_mov_b32 s14, s18
	s_mov_b32 s15, s10
	v_mov_b32_e32 v82, v74
	v_mov_b32_e32 v83, v131
	v_lshl_add_u64 v[84:85], s[14:15], 0, v[82:83]
	v_lshlrev_b64 v[74:75], 10, v[72:73]
	v_lshl_add_u64 v[82:83], v[84:85], 0, v[74:75]
	global_load_dwordx4 v[86:89], v[82:83], off
	v_add_u32_e32 v73, 0x800, v72
	v_ashrrev_i32_e32 v72, 31, v73
	v_mov_b32_e32 v74, v73
	v_mov_b32_e32 v75, v72
	v_lshlrev_b64 v[82:83], 10, v[74:75]
	v_lshl_add_u64 v[72:73], v[84:85], 0, v[82:83]
	global_load_dwordx4 v[82:85], v[72:73], off
	v_bfe_u32 v72, v1, 4, 2
	v_and_b32_e32 v73, 15, v1
	v_lshlrev_b32_e32 v74, 4, v72
	v_mov_b32_e32 v72, v131
	v_mov_b32_e32 v75, v131
	v_mov_b32_e32 v76, v131
	v_lshlrev_b32_e32 v78, 6, v73
	v_or_b32_e32 v90, 0x800, v78
	v_lshlrev_b32_e32 v91, 1, v90
	v_mov_b32_e32 v90, v131
	v_mov_b32_e32 v92, v131
	s_lshl_b32 s10, s1, 6
	v_readlane_b32 s11, v253, 41
	v_readlane_b32 s14, v253, 42
	s_mov_b32 s18, s11
	s_mov_b32 s19, s14
	v_mov_b32_e32 v94, v74
	v_mov_b32_e32 v95, v131
	v_lshl_add_u64 v[96:97], s[18:19], 0, v[94:95]
	v_lshlrev_b32_e32 v74, 7, v73
	v_or_b32_e32 v93, 0x2000, v74
	v_mov_b32_e32 v94, v74
	v_mov_b32_e32 v95, v131
	v_lshl_add_u64 v[98:99], v[96:97], 0, v[94:95]
	v_mov_b32_e32 v94, v93
	v_mov_b32_e32 v95, v72
	v_lshl_add_u64 v[100:101], v[96:97], 0, v[94:95]
	v_and_b32_e32 v251, 15, v0
	v_mul_u32_u24_e32 v251, 0x90, v251
	v_bfe_u32 v250, v0, 4, 2
	v_lshl_add_u32 v251, v250, 4, v251
	v_add_u32_e32 v251, 0x4000, v251
	ds_read_b128 v[102:105], v251
	ds_read_b128 v[106:109], v251 offset:9216
	v_or_b32_e32 v94, 0x2800, v74
	ds_read_b128 v[110:113], v251 offset:2304
	v_or_b32_e32 v95, 0x3000, v74
	v_or_b32_e32 v100, 0xc00, v78
	v_lshlrev_b32_e32 v78, 1, v100
	v_or_b32_e32 v100, 0x3800, v74
	v_mov_b32_e32 v114, v91
	v_mov_b32_e32 v115, v90
	v_lshl_add_u64 v[116:117], v[96:97], 0, v[114:115]
	v_mov_b32_e32 v114, v78
	v_mov_b32_e32 v115, v92
	v_lshl_add_u64 v[118:119], v[96:97], 0, v[114:115]
	ds_read_b128 v[120:123], v251 offset:4608
	v_lshl_add_u64 v[114:115], v[96:97], 0, 64
	ds_read_b128 v[124:127], v251 offset:6912
	s_mov_b32 s11, 0x8000
	s_mov_b32 s14, 0xc000
	v_mov_b32_e32 v116, v94
	v_mov_b32_e32 v117, v75
	v_lshl_add_u64 v[118:119], v[96:97], 0, v[116:117]
	ds_read_b128 v[138:141], v251 offset:11520
	v_mov_b32_e32 v116, v95
	v_mov_b32_e32 v117, v76
	v_lshl_add_u64 v[118:119], v[96:97], 0, v[116:117]
	ds_read_b128 v[142:145], v251 offset:13824
	v_mov_b32_e32 v116, v100
	v_mov_b32_e32 v117, v131
	v_lshl_add_u64 v[118:119], v[96:97], 0, v[116:117]
	ds_read_b128 v[146:149], v251 offset:16128
	ds_read_b128 v[116:119], v251 offset:64
	ds_read_b128 v[150:153], v251 offset:2368
	v_mov_b32_e32 v96, v93
	v_mov_b32_e32 v97, v72
	v_lshl_add_u64 v[98:99], v[114:115], 0, v[96:97]
	v_mul_u32_u24_e32 v72, s1, v73
	v_mov_b32_e32 v96, v91
	v_mov_b32_e32 v97, v90
	v_lshl_add_u64 v[128:129], v[114:115], 0, v[96:97]
	ds_read_b128 v[154:157], v251 offset:4672
	ds_read_b128 v[162:165], v251 offset:9280
	v_mov_b32_e32 v90, v78
	v_mov_b32_e32 v91, v92
	v_lshl_add_u64 v[96:97], v[114:115], 0, v[90:91]
	ds_read_b128 v[90:93], v251 offset:6976
	v_mov_b32_e32 v96, v94
	v_mov_b32_e32 v97, v75
	v_lshl_add_u64 v[98:99], v[114:115], 0, v[96:97]
	ds_read_b128 v[168:171], v251 offset:11584
	v_readlane_b32 s15, v253, 39
	v_readlane_b32 s18, v253, 40
	v_mov_b32_e32 v74, v95
	v_mov_b32_e32 v75, v76
	v_lshl_add_u64 v[96:97], v[114:115], 0, v[74:75]
	ds_read_b128 v[174:177], v251 offset:13888
	v_mov_b32_e32 v74, v100
	v_mov_b32_e32 v75, v131
	v_lshl_add_u64 v[94:95], v[114:115], 0, v[74:75]
	v_lshlrev_b32_e32 v73, 2, v72
	s_mov_b32 s62, s15
	s_mov_b32 s63, s18
	v_mov_b32_e32 v74, v73
	v_mov_b32_e32 v75, v131
	v_lshl_add_u64 v[96:97], s[62:63], 0, v[74:75]
	v_add_co_u32_e32 v72, vcc, s11, v96
	ds_read_b128 v[98:101], v251 offset:16192
	s_nop 0
	v_addc_co_u32_e32 v73, vcc, 0, v97, vcc
	v_add_co_u32_e32 v74, vcc, s14, v96
	global_load_dword v75, v[72:73], off offset:128
	s_nop 0
	v_addc_co_u32_e32 v72, vcc, 0, v97, vcc
	v_mov_b32_e32 v94, v74
	v_mov_b32_e32 v95, v72
	global_load_dword v73, v[94:95], off offset:128
	s_mov_b32 s18, s10
	s_mov_b32 s19, s89
	v_lshl_add_u64 v[94:95], v[96:97], 0, s[18:19]
	v_add_co_u32_e32 v72, vcc, s11, v94
	s_nop 1
	v_addc_co_u32_e32 v74, vcc, 0, v95, vcc
	v_add_co_u32_e32 v76, vcc, s14, v94
	s_nop 1
	v_addc_co_u32_e32 v78, vcc, 0, v95, vcc
	v_mov_b32_e32 v96, v72
	v_mov_b32_e32 v97, v74
	global_load_dword v114, v[96:97], off offset:128
	v_mov_b32_e32 v96, v76
	v_mov_b32_e32 v97, v78
	global_load_dword v72, v[96:97], off offset:128
	s_mov_b32 s18, s10
	s_mov_b32 s19, s89
	v_lshl_add_u64 v[96:97], v[94:95], 0, s[18:19]
	v_add_co_u32_e32 v74, vcc, s11, v96
	s_nop 1
	v_addc_co_u32_e32 v76, vcc, 0, v97, vcc
	v_add_co_u32_e32 v78, vcc, s14, v96
	s_nop 1
	v_addc_co_u32_e32 v94, vcc, 0, v97, vcc
	v_mov_b32_e32 v128, v74
	v_mov_b32_e32 v129, v76
	global_load_dword v95, v[128:129], off offset:128
	v_mov_b32_e32 v128, v78
	v_mov_b32_e32 v129, v94
	global_load_dword v74, v[128:129], off offset:128
	s_mov_b32 s18, s10
	s_mov_b32 s19, s89
	v_lshl_add_u64 v[128:129], v[96:97], 0, s[18:19]
	v_add_co_u32_e32 v76, vcc, s11, v128
	s_nop 1
	v_addc_co_u32_e32 v78, vcc, 0, v129, vcc
	v_add_co_u32_e32 v94, vcc, s14, v128
	s_nop 1
	v_addc_co_u32_e32 v96, vcc, 0, v129, vcc
	v_mov_b32_e32 v128, v76
	v_mov_b32_e32 v129, v78
	global_load_dword v97, v[128:129], off offset:128
	v_mov_b32_e32 v128, v94
	v_mov_b32_e32 v129, v96
	global_load_dword v76, v[128:129], off offset:128
	v_lshlrev_b32_e32 v2, 3, v1
	s_or_b32 s0, s1, s0
	s_lshl_b32 s3, s2, 1
	v_readlane_b32 s6, v253, 53
	v_and_b32_e32 v10, 56, v2
	v_and_b32_e32 v2, 0xffffffc0, v2
	v_readlane_b32 s7, v253, 54
	s_add_u32 s4, s6, s3
	v_add_u32_e32 v8, s0, v2
	s_addc_u32 s5, s7, 0
	v_lshlrev_b32_e32 v130, 1, v10
	v_ashrrev_i32_e32 v9, 31, v8
	v_lshl_add_u64 v[6:7], s[4:5], 0, v[130:131]
	v_lshlrev_b64 v[2:3], 10, v[8:9]
	v_lshl_add_u64 v[2:3], v[6:7], 0, v[2:3]
	v_add_u32_e32 v8, 0x800, v8
	v_ashrrev_i32_e32 v9, 31, v8
	v_lshlrev_b64 v[8:9], 10, v[8:9]
	v_lshl_add_u64 v[6:7], v[6:7], 0, v[8:9]
	v_ashrrev_i32_e32 v11, 3, v1
	v_lshlrev_b32_e32 v11, 1, v11
	s_movk_i32 s3, 0x90
	v_mad_u32_u24 v11, v10, s3, v11
	s_barrier
	v_bfe_u32 v41, v1, 4, 2
	v_and_b32_e32 v40, 15, v1
	v_lshlrev_b32_e32 v130, 4, v41
	v_mov_b32_e32 v37, v131
	v_mov_b32_e32 v63, v131
	v_mov_b32_e32 v65, v131
	v_lshlrev_b32_e32 v39, 6, v40
	v_or_b32_e32 v38, 0x800, v39
	v_lshlrev_b32_e32 v32, 1, v38
	v_mov_b32_e32 v33, v131
	v_mov_b32_e32 v35, v131
	s_lshl_b32 s88, s1, 6
	s_waitcnt vmcnt(0) lgkmcnt(0)
	ds_write_b16 v11, v86
	ds_write_b16_d16_hi v11, v86 offset:144
	ds_write_b16 v11, v87 offset:288
	ds_write_b16_d16_hi v11, v87 offset:432
	ds_write_b16 v11, v88 offset:576
	ds_write_b16_d16_hi v11, v88 offset:720
	ds_write_b16 v11, v89 offset:864
	ds_write_b16_d16_hi v11, v89 offset:1008
	v_add_u32_e32 v2, 0x100, v1
	v_ashrrev_i32_e32 v2, 3, v2
	v_lshlrev_b32_e32 v2, 1, v2
	v_mad_u32_u24 v2, v10, s3, v2
	ds_write_b16 v2, v82
	ds_write_b16_d16_hi v2, v82 offset:144
	ds_write_b16 v2, v83 offset:288
	ds_write_b16_d16_hi v2, v83 offset:432
	ds_write_b16 v2, v84 offset:576
	ds_write_b16_d16_hi v2, v84 offset:720
	ds_write_b16 v2, v85 offset:864
	ds_write_b16_d16_hi v2, v85 offset:1008
	v_ashrrev_i32_e32 v2, 2, v1
	v_bfi_b32 v1, -16, v2, v1
	v_mad_u64_u32 v[18:19], s[4:5], v1, s3, v[130:131]
	v_readlane_b32 s4, v253, 41
	v_readlane_b32 s5, v253, 42
	s_waitcnt lgkmcnt(0)
	s_barrier
	v_lshl_add_u64 v[20:21], s[4:5], 0, v[130:131]
	v_lshlrev_b32_e32 v130, 7, v40
	v_or_b32_e32 v36, 0x2000, v130
	v_lshl_add_u64 v[30:31], v[20:21], 0, v[130:131]
	v_lshl_add_u64 v[26:27], v[20:21], 0, v[36:37]
	v_and_b32_e32 v68, -16, v2
	ds_read_b128 v[2:5], v18
	ds_read_b128 v[58:61], v18 offset:64
	v_or_b32_e32 v62, 0x2800, v130
	v_or_b32_e32 v64, 0x3000, v130
	v_or_b32_e32 v1, 0xc00, v39
	v_lshlrev_b32_e32 v34, 1, v1
	v_or_b32_e32 v130, 0x3800, v130
	v_lshl_add_u64 v[14:15], v[20:21], 0, v[32:33]
	v_lshl_add_u64 v[22:23], v[20:21], 0, v[34:35]
	v_lshl_add_u64 v[66:67], v[20:21], 0, 64
	s_mov_b32 s4, 0x8000
	s_mov_b32 s5, 0xc000
	s_waitcnt lgkmcnt(1)
	v_mfma_f32_16x16x32_bf16 v[6:9], v[2:5], v[102:105], 0
	v_mfma_f32_16x16x32_bf16 v[42:45], v[2:5], v[106:109], 0
	v_lshl_add_u64 v[26:27], v[20:21], 0, v[62:63]
	v_mfma_f32_16x16x32_bf16 v[10:13], v[2:5], v[110:113], 0
	v_mfma_f32_16x16x32_bf16 v[14:17], v[2:5], v[120:123], 0
	v_mfma_f32_16x16x32_bf16 v[22:25], v[2:5], v[124:127], 0
	v_mfma_f32_16x16x32_bf16 v[46:49], v[2:5], v[138:141], 0
	v_lshl_add_u64 v[26:27], v[20:21], 0, v[64:65]
	v_mfma_f32_16x16x32_bf16 v[50:53], v[2:5], v[142:145], 0
	v_lshl_add_u64 v[26:27], v[20:21], 0, v[130:131]
	v_mfma_f32_16x16x32_bf16 v[54:57], v[2:5], v[146:149], 0
	s_waitcnt lgkmcnt(0)
	v_mfma_f32_16x16x32_bf16 v[26:29], v[58:61], v[116:119], v[6:9]
	s_nop 1
	v_lshl_add_u64 v[6:7], v[66:67], 0, v[36:37]
	v_mul_u32_u24_e32 v36, s1, v40
	v_mfma_f32_16x16x32_bf16 v[18:21], v[58:61], v[150:153], v[10:13]
	v_lshl_add_u64 v[2:3], v[66:67], 0, v[32:33]
	s_nop 0
	v_mfma_f32_16x16x32_bf16 v[10:13], v[58:61], v[154:157], v[14:17]
	v_lshl_add_u64 v[2:3], v[66:67], 0, v[34:35]
	v_add_u32_e32 v34, s2, v68
	v_mfma_f32_16x16x32_bf16 v[30:33], v[58:61], v[162:165], v[42:45]
	v_lshl_add_u64 v[6:7], v[66:67], 0, v[62:63]
	v_readlane_b32 s2, v253, 39
	v_readlane_b32 s3, v253, 40
	v_lshl_or_b32 v34, v41, 2, v34
	v_ashrrev_i32_e32 v35, 31, v34
	v_mfma_f32_16x16x32_bf16 v[2:5], v[58:61], v[90:93], v[22:25]
	v_mfma_f32_16x16x32_bf16 v[22:25], v[58:61], v[168:171], v[46:49]
	v_lshl_add_u64 v[6:7], v[66:67], 0, v[64:65]
	v_mfma_f32_16x16x32_bf16 v[14:17], v[58:61], v[174:177], v[50:53]
	v_lshl_add_u64 v[6:7], v[66:67], 0, v[130:131]
	v_lshlrev_b32_e32 v130, 2, v36
	v_lshl_add_u64 v[36:37], s[2:3], 0, v[130:131]
	v_add_co_u32_e32 v40, vcc, s4, v36
	s_nop 0
	v_addc_co_u32_e32 v41, vcc, 0, v37, vcc
	v_add_co_u32_e32 v42, vcc, s5, v36
	v_mov_b32_e32 v40, v75
	s_nop 0
	v_addc_co_u32_e32 v43, vcc, 0, v37, vcc
	v_mov_b32_e32 v42, v73
	v_readlane_b32 s2, v254, 7
	v_readlane_b32 s3, v254, 8
	v_mfma_f32_16x16x32_bf16 v[6:9], v[58:61], v[98:101], v[54:57]
	v_pk_mul_f32 v[44:45], v[30:31], v[42:43] op_sel_hi:[1,0]
	s_nop 0
	v_pk_fma_f32 v[44:45], v[26:27], v[40:41], v[44:45] op_sel_hi:[1,0,1]
	v_pk_mul_f32 v[26:27], v[26:27], v[42:43] op_sel_hi:[1,0]
	s_nop 0
	v_pk_fma_f32 v[30:31], v[30:31], v[40:41], v[26:27] op_sel_hi:[1,0,1] neg_lo:[0,0,1] neg_hi:[0,0,1]
	v_pk_mul_f32 v[26:27], v[32:33], v[42:43] op_sel_hi:[1,0]
	v_cvt_pk_bf16_f32 v30, v30, v31
	v_pk_fma_f32 v[46:47], v[28:29], v[40:41], v[26:27] op_sel_hi:[1,0,1]
	v_pk_mul_f32 v[26:27], v[28:29], v[42:43] op_sel_hi:[1,0]
	s_nop 0
	v_pk_fma_f32 v[28:29], v[32:33], v[40:41], v[26:27] op_sel_hi:[1,0,1] neg_lo:[0,0,1] neg_hi:[0,0,1]
	v_or_b32_e32 v26, s0, v39
	v_ashrrev_i32_e32 v27, 31, v26
	v_lshlrev_b64 v[32:33], 9, v[26:27]
	v_lshl_add_u64 v[32:33], v[32:33], 0, v[34:35]
	v_lshlrev_b64 v[32:33], 1, v[32:33]
	v_cvt_pk_bf16_f32 v31, v28, v29
	v_lshl_add_u64 v[28:29], s[2:3], 0, v[32:33]
	global_store_dwordx2 v[28:29], v[30:31], off
	v_lshl_add_u64 v[28:29], v[36:37], 0, s[88:89]
	v_add_co_u32_e32 v30, vcc, s4, v28
	v_cvt_pk_bf16_f32 v40, v44, v45
	s_nop 0
	v_addc_co_u32_e32 v31, vcc, 0, v29, vcc
	v_cvt_pk_bf16_f32 v41, v46, v47
	v_lshl_add_u64 v[42:43], s[6:7], 0, v[32:33]
	v_add_co_u32_e32 v32, vcc, s5, v28
	global_store_dwordx2 v[42:43], v[40:41], off
	s_nop 0
	v_addc_co_u32_e32 v33, vcc, 0, v29, vcc
	v_mov_b32_e32 v30, v114
	s_nop 0
	v_mov_b32_e32 v32, v72
	v_pk_mul_f32 v[36:37], v[22:23], v[32:33] op_sel_hi:[1,0]
	s_nop 0
	v_pk_fma_f32 v[36:37], v[18:19], v[30:31], v[36:37] op_sel_hi:[1,0,1]
	v_pk_mul_f32 v[18:19], v[18:19], v[32:33] op_sel_hi:[1,0]
	s_nop 0
	v_pk_fma_f32 v[18:19], v[22:23], v[30:31], v[18:19] op_sel_hi:[1,0,1] neg_lo:[0,0,1] neg_hi:[0,0,1]
	v_pk_mul_f32 v[22:23], v[24:25], v[32:33] op_sel_hi:[1,0]
	v_cvt_pk_bf16_f32 v18, v18, v19
	v_pk_fma_f32 v[22:23], v[20:21], v[30:31], v[22:23] op_sel_hi:[1,0,1]
	v_pk_mul_f32 v[20:21], v[20:21], v[32:33] op_sel_hi:[1,0]
	v_cvt_pk_bf16_f32 v27, v22, v23
	v_pk_fma_f32 v[20:21], v[24:25], v[30:31], v[20:21] op_sel_hi:[1,0,1] neg_lo:[0,0,1] neg_hi:[0,0,1]
	v_or_b32_e32 v24, 0x400, v26
	v_ashrrev_i32_e32 v25, 31, v24
	v_lshlrev_b64 v[24:25], 9, v[24:25]
	v_lshl_add_u64 v[24:25], v[24:25], 0, v[34:35]
	v_lshlrev_b64 v[22:23], 1, v[24:25]
	v_cvt_pk_bf16_f32 v19, v20, v21
	v_lshl_add_u64 v[20:21], s[2:3], 0, v[22:23]
	global_store_dwordx2 v[20:21], v[18:19], off
	v_lshl_add_u64 v[18:19], v[28:29], 0, s[88:89]
	v_add_co_u32_e32 v20, vcc, s4, v18
	v_cvt_pk_bf16_f32 v26, v36, v37
	s_nop 0
	v_addc_co_u32_e32 v21, vcc, 0, v19, vcc
	v_lshl_add_u64 v[24:25], s[6:7], 0, v[22:23]
	v_add_co_u32_e32 v22, vcc, s5, v18
	global_store_dwordx2 v[24:25], v[26:27], off
	s_nop 0
	v_addc_co_u32_e32 v23, vcc, 0, v19, vcc
	v_mov_b32_e32 v20, v95
	s_nop 0
	v_mov_b32_e32 v22, v74
	v_pk_mul_f32 v[24:25], v[14:15], v[22:23] op_sel_hi:[1,0]
	s_nop 0
	v_pk_fma_f32 v[24:25], v[10:11], v[20:21], v[24:25] op_sel_hi:[1,0,1]
	v_pk_mul_f32 v[10:11], v[10:11], v[22:23] op_sel_hi:[1,0]
	s_nop 0
	v_pk_fma_f32 v[10:11], v[14:15], v[20:21], v[10:11] op_sel_hi:[1,0,1] neg_lo:[0,0,1] neg_hi:[0,0,1]
	v_pk_mul_f32 v[14:15], v[16:17], v[22:23] op_sel_hi:[1,0]
	v_cvt_pk_bf16_f32 v10, v10, v11
	v_pk_fma_f32 v[14:15], v[12:13], v[20:21], v[14:15] op_sel_hi:[1,0,1]
	v_pk_mul_f32 v[12:13], v[12:13], v[22:23] op_sel_hi:[1,0]
	s_nop 0
	v_pk_fma_f32 v[12:13], v[16:17], v[20:21], v[12:13] op_sel_hi:[1,0,1] neg_lo:[0,0,1] neg_hi:[0,0,1]
	v_or_b32_e32 v16, s0, v38
	v_ashrrev_i32_e32 v17, 31, v16
	v_lshlrev_b64 v[16:17], 9, v[16:17]
	v_lshl_add_u64 v[16:17], v[16:17], 0, v[34:35]
	v_cvt_pk_bf16_f32 v21, v14, v15
	v_lshlrev_b64 v[14:15], 1, v[16:17]
	v_cvt_pk_bf16_f32 v11, v12, v13
	v_lshl_add_u64 v[12:13], s[2:3], 0, v[14:15]
	global_store_dwordx2 v[12:13], v[10:11], off
	v_lshl_add_u64 v[10:11], v[18:19], 0, s[88:89]
	v_add_co_u32_e32 v12, vcc, s4, v10
	v_cvt_pk_bf16_f32 v20, v24, v25
	s_nop 0
	v_addc_co_u32_e32 v13, vcc, 0, v11, vcc
	v_lshl_add_u64 v[16:17], s[6:7], 0, v[14:15]
	v_add_co_u32_e32 v10, vcc, s5, v10
	global_store_dwordx2 v[16:17], v[20:21], off
	s_nop 0
	v_addc_co_u32_e32 v11, vcc, 0, v11, vcc
	v_mov_b32_e32 v12, v97
	s_nop 0
	v_mov_b32_e32 v10, v76
	v_pk_mul_f32 v[14:15], v[6:7], v[10:11] op_sel_hi:[1,0]
	s_nop 0
	v_pk_fma_f32 v[14:15], v[2:3], v[12:13], v[14:15] op_sel_hi:[1,0,1]
	v_pk_mul_f32 v[2:3], v[2:3], v[10:11] op_sel_hi:[1,0]
	s_nop 0
	v_pk_fma_f32 v[2:3], v[6:7], v[12:13], v[2:3] op_sel_hi:[1,0,1] neg_lo:[0,0,1] neg_hi:[0,0,1]
	v_pk_mul_f32 v[6:7], v[8:9], v[10:11] op_sel_hi:[1,0]
	v_cvt_pk_bf16_f32 v2, v2, v3
	v_pk_fma_f32 v[6:7], v[4:5], v[12:13], v[6:7] op_sel_hi:[1,0,1]
	v_pk_mul_f32 v[4:5], v[4:5], v[10:11] op_sel_hi:[1,0]
	v_cvt_pk_bf16_f32 v11, v6, v7
	v_pk_fma_f32 v[4:5], v[8:9], v[12:13], v[4:5] op_sel_hi:[1,0,1] neg_lo:[0,0,1] neg_hi:[0,0,1]
	v_or_b32_e32 v8, s0, v1
	v_ashrrev_i32_e32 v9, 31, v8
	v_lshlrev_b64 v[8:9], 9, v[8:9]
	v_lshl_add_u64 v[8:9], v[8:9], 0, v[34:35]
	v_lshlrev_b64 v[6:7], 1, v[8:9]
	v_cvt_pk_bf16_f32 v10, v14, v15
	v_lshl_add_u64 v[8:9], s[6:7], 0, v[6:7]
	v_cvt_pk_bf16_f32 v3, v4, v5
	v_lshl_add_u64 v[4:5], s[2:3], 0, v[6:7]
	global_store_dwordx2 v[8:9], v[10:11], off
	global_store_dwordx2 v[4:5], v[2:3], off
